# P10 epilogue: conv weights/bias staged through LDS per unit + row scales prefetched at unit header (no vmcnt wait before the epilogue VALU)
# speedup vs baseline: 1.1060x; 1.0026x over previous
.LBB0_876:
	s_mov_b32 s98, 0
	s_cmp_eq_u32 s8, 1
	s_cselect_b32 s98, 0x5600, s98
	s_cmp_eq_u32 s8, 2
	s_cselect_b32 s98, 0xac00, s98
	s_cmp_eq_u32 s8, 4
	s_cselect_b32 s98, 0x2b00, s98
	s_cmp_eq_u32 s8, 5
	s_cselect_b32 s98, 0x8100, s98
	s_cmp_eq_u32 s8, 6
	s_cselect_b32 s98, 0xd700, s98
	s_cmp_eq_u32 s8, 7
	s_cselect_b32 s98, 0x2b00, s98
	s_and_b32 s99, s8, 3
	s_cmp_eq_u32 s99, 3
	s_cselect_b32 s100, s48, s46
	s_cselect_b32 s101, s49, s47
	s_add_u32 s98, s100, s98
	s_addc_u32 s99, s101, 0
	v_mbcnt_lo_u32_b32 v254, -1, 0
	v_mbcnt_hi_u32_b32 v254, -1, v254
	s_lshl_b32 s100, s8, 9
	v_lshlrev_b32_e32 v254, 3, v254
	s_add_i32 s100, s100, 0x22c00
	v_add_u32_e32 v241, s100, v254
	s_lshl_b32 s8, s8, 5
	s_and_b32 s26, s8, 0x60
	s_lshl_b32 s22, s7, 13
	s_lshl_b32 s23, s26, 7
	s_add_u32 s8, s30, 0x4b0000
	s_mov_b64 s[10:11], 0x80
	s_addc_u32 s9, s31, 0
	s_add_i32 m0, s71, 0x18000
	v_lshl_add_u64 v[6:7], v[6:7], 0, s[10:11]
	s_waitcnt vmcnt(2)
	s_barrier
	global_load_lds_dwordx4 v[6:7], off
	v_lshl_add_u64 v[4:5], v[4:5], 0, s[10:11]
	s_add_i32 m0, s71, 0x1a000
	s_add_i32 s78, s71, 0x8000
	s_add_i32 s79, s71, 0xa000
	global_load_lds_dwordx4 v[4:5], off
	v_lshl_add_u64 v[2:3], v[2:3], 0, s[10:11]
	s_mov_b32 m0, s78
	s_add_u32 s18, s64, 0x40080
	global_load_lds_dwordx4 v[2:3], off
	v_lshl_add_u64 v[0:1], v[0:1], 0, s[10:11]
	s_mov_b32 m0, s79
	s_addc_u32 s19, s65, 0
	global_load_lds_dwordx4 v[0:1], off
	s_add_i32 m0, s71, 0x1c000
	v_lshl_add_u64 v[0:1], s[18:19], 0, v[138:139]
	global_load_lds_dwordx4 v[0:1], off
	v_lshl_add_u64 v[0:1], s[18:19], 0, v[142:143]
	s_add_i32 m0, s71, 0x1e000
	v_and_b32_e32 v234, 15, v8
	global_load_lds_dwordx4 v[0:1], off
	v_lshrrev_b32_e32 v0, 1, v8
	s_cmpk_lt_u32 s6, 0x100
	v_and_b32_e32 v0, 24, v0
	v_lshlrev_b32_e32 v1, 6, v234
	v_lshlrev_b32_e32 v2, 2, v8
	s_cselect_b64 s[18:19], -1, 0
	s_lshl_b32 s81, s7, 2
	v_lshl_or_b32 v1, v0, 1, v1
	v_and_b32_e32 v2, 32, v2
	s_ashr_i32 s82, s81, 31
	v_bitop3_b32 v3, v1, s22, v2 bitop3:0xde
	s_add_u32 s22, s46, 0x5600
	v_bitop3_b32 v235, v1, s23, v2 bitop3:0xde
	s_addc_u32 s23, s47, 0
	s_add_u32 s24, s46, 0xac00
	v_lshlrev_b32_e32 v1, 3, v234
	s_addc_u32 s25, s47, 0
	v_lshl_or_b32 v236, s7, 7, v1
	s_add_u32 s36, s46, 0x2b00
	v_and_b32_e32 v1, 1, v9
	s_addc_u32 s37, s47, 0
	v_or_b32_e32 v237, s26, v0
	v_add3_u32 v0, v11, v12, v13
	v_lshlrev_b32_e32 v1, 6, v1
	s_add_u32 s38, s46, 0x8100
	v_lshl_or_b32 v0, v0, 11, v1
	s_addc_u32 s39, s47, 0
	v_lshl_add_u32 v0, v10, 1, v0
	v_mov_b32_e32 v1, v139
	s_mov_b64 s[6:7], 0x2080
	s_add_u32 s40, s46, 0xd700
	v_lshl_add_u64 v[144:145], v[0:1], 0, s[6:7]
	v_and_b32_e32 v1, 1, v14
	s_addc_u32 s41, s47, 0
	v_add3_u32 v0, v16, v17, v18
	v_lshlrev_b32_e32 v1, 6, v1
	s_waitcnt vmcnt(6)
	s_add_u32 s42, s48, 0x2b00
	v_lshl_or_b32 v0, v0, 11, v1
	s_addc_u32 s43, s49, 0
	v_lshl_add_u32 v0, v15, 1, v0
	v_mov_b32_e32 v1, v139
	s_add_i32 s88, 0, 0x10000
	s_add_i32 s89, 0, 0x14000
	s_mov_b32 s80, 0x8000
	v_lshl_add_u64 v[146:147], v[0:1], 0, s[6:7]
	v_mov_b64_e32 v[148:149], 0xb00
	v_mov_b64_e32 v[150:151], 0xaff
	s_movk_i32 s83, 0x161
	v_add_u32_e32 v238, s88, v235
	v_add_u32_e32 v239, s89, v235
	v_add_u32_e32 v240, 0, v3
	s_mov_b64 s[44:45], 0x5800
	s_movk_i32 s90, 0x5000
	s_movk_i32 s91, 0x1000
	s_movk_i32 s92, 0xac0
	s_movk_i32 s93, 0x1600
	s_barrier
	s_branch .LBB0_879

.LBB0_879:
	v_lshrrev_b32_e32 v244, 2, v254
	v_lshl_add_u32 v244, s60, 7, v244
	v_mov_b32_e32 v226, 0
	v_mov_b32_e32 v227, 0
	v_lshl_add_u32 v245, s60, 9, v254
	v_cmp_gt_u32_e32 vcc, 0xac0, v244
	v_lshl_add_u32 v246, s58, 8, v236
	v_lshlrev_b32_e32 v246, 2, v246
	s_and_saveexec_b64 s[100:101], vcc
	global_load_dwordx2 v[226:227], v245, s[98:99]
	s_mov_b64 exec, s[100:101]
	global_load_dwordx4 v[218:221], v246, s[8:9]
	global_load_dwordx4 v[222:225], v246, s[8:9] offset:16
	s_add_i32 s76, s76, 1
	s_mul_i32 s6, s76, s21
	s_mul_hi_u32 s7, s76, s20
	s_add_i32 s7, s7, s6
	s_mul_i32 s6, s76, s20
	s_add_u32 s54, s6, s2
	s_addc_u32 s55, s7, s3
	v_cmp_gt_i64_e32 vcc, s[54:55], v[150:151]
	v_cmp_lt_i64_e64 s[6:7], s[54:55], v[148:149]
	s_cbranch_vccnz .LBB0_881
	s_ashr_i32 s26, s54, 31
	s_lshr_b32 s26, s26, 29
	s_add_i32 s26, s54, s26
	s_ashr_i32 s27, s26, 3
	s_and_b32 s26, s26, -8
	s_sub_i32 s26, s54, s26
	s_cmp_lt_i32 s26, 0
	s_cselect_b32 s50, s83, 0x160
	s_mul_i32 s26, s26, s50
	s_add_i32 s26, s26, s27
	s_mul_hi_i32 s27, s26, 0x3e0f83e1
	s_lshr_b32 s50, s27, 31
	s_ashr_i32 s27, s27, 5
	s_add_i32 s27, s27, s50
	s_mul_i32 s51, s27, 6
	s_sub_i32 s50, 0x80, s51
	s_min_i32 s52, s50, 6
	s_abs_i32 s50, s52
	v_cvt_f32_u32_e32 v0, s50
	s_sub_i32 s54, 0, s50
	s_mulk_i32 s27, 0x84
	s_sub_i32 s26, s26, s27
	v_rcp_iflag_f32_e32 v0, v0
	s_abs_i32 s27, s26
	s_xor_b32 s53, s26, s52
	s_ashr_i32 s53, s53, 31
	v_mul_f32_e32 v0, 0x4f7ffffe, v0
	v_cvt_u32_f32_e32 v0, v0
	s_nop 0
	v_readfirstlane_b32 s55, v0
	s_mul_i32 s54, s54, s55
	s_mul_hi_u32 s54, s55, s54
	s_add_i32 s55, s55, s54
	s_mul_hi_u32 s54, s27, s55
	s_mul_i32 s55, s54, s50
	s_sub_i32 s27, s27, s55
	s_add_i32 s56, s54, 1
	s_sub_i32 s55, s27, s50
	s_cmp_ge_u32 s27, s50
	s_cselect_b32 s54, s56, s54
	s_cselect_b32 s27, s55, s27
	s_add_i32 s55, s54, 1
	s_cmp_ge_u32 s27, s50
	s_cselect_b32 s27, s55, s54
	s_xor_b32 s27, s27, s53
	s_sub_i32 s50, s27, s53
	s_mul_i32 s27, s50, s52
	s_sub_i32 s26, s26, s27
	s_add_i32 s52, s51, s26

.LBB0_882:
	ds_read_b128 v[64:67], v238
	ds_read_b128 v[68:71], v238 offset:1024
	ds_read_b128 v[152:155], v238 offset:2048
	ds_read_b128 v[156:159], v238 offset:3072
	ds_read_b128 v[160:163], v239
	ds_read_b128 v[164:167], v239 offset:1024
	ds_read_b128 v[168:171], v239 offset:2048
	ds_read_b128 v[172:175], v239 offset:3072
	s_add_u32 s64, s62, 0x100
	s_addc_u32 s65, s63, 0
	s_cmp_eq_u32 s96, 12
	s_cselect_b32 s69, s53, s65
	s_cselect_b32 s68, s59, s64
	s_cselect_b32 s67, s51, s95
	s_cselect_b32 s66, s61, s94
	v_lshl_add_u64 v[208:209], s[62:63], 0, v[144:145]
	s_add_i32 m0, s71, 0xc000
	ds_read_b128 v[176:179], v240
	ds_read_b128 v[180:183], v240 offset:1024
	ds_read_b128 v[184:187], v240 offset:2048
	ds_read_b128 v[188:191], v240 offset:3072
	ds_read_b128 v[192:195], v240 offset:4096
	ds_read_b128 v[196:199], v240 offset:5120
	ds_read_b128 v[200:203], v240 offset:6144
	ds_read_b128 v[204:207], v240 offset:7168
	global_load_lds_dwordx4 v[208:209], off
	v_lshl_add_u64 v[208:209], s[62:63], 0, v[146:147]
	s_add_i32 m0, s71, 0xe000
	s_nop 0
	global_load_lds_dwordx4 v[208:209], off
	s_waitcnt vmcnt(8)
	s_waitcnt lgkmcnt(0)
	s_barrier
	s_setprio 1
	s_waitcnt lgkmcnt(0)
	v_mfma_f32_16x16x32_bf16 v[104:107], v[64:67], v[176:179], v[104:107]
	v_mfma_f32_16x16x32_bf16 v[96:99], v[152:155], v[176:179], v[96:99]
	v_mfma_f32_16x16x32_bf16 v[92:95], v[64:67], v[184:187], v[92:95]
	v_mfma_f32_16x16x32_bf16 v[88:91], v[152:155], v[184:187], v[88:91]
	v_mfma_f32_16x16x32_bf16 v[60:63], v[64:67], v[192:195], v[60:63]
	v_mfma_f32_16x16x32_bf16 v[28:31], v[152:155], v[192:195], v[28:31]
	v_mfma_f32_16x16x32_bf16 v[56:59], v[64:67], v[200:203], v[56:59]
	v_mfma_f32_16x16x32_bf16 v[24:27], v[152:155], v[200:203], v[24:27]
	v_mfma_f32_16x16x32_bf16 v[104:107], v[68:71], v[180:183], v[104:107]
	v_mfma_f32_16x16x32_bf16 v[96:99], v[156:159], v[180:183], v[96:99]
	v_mfma_f32_16x16x32_bf16 v[92:95], v[68:71], v[188:191], v[92:95]
	v_mfma_f32_16x16x32_bf16 v[88:91], v[156:159], v[188:191], v[88:91]
	v_mfma_f32_16x16x32_bf16 v[60:63], v[68:71], v[196:199], v[60:63]
	v_mfma_f32_16x16x32_bf16 v[28:31], v[156:159], v[196:199], v[28:31]
	v_mfma_f32_16x16x32_bf16 v[56:59], v[68:71], v[204:207], v[56:59]
	v_mfma_f32_16x16x32_bf16 v[24:27], v[156:159], v[204:207], v[24:27]
	s_setprio 0
	s_setprio 1
	v_mfma_f32_16x16x32_bf16 v[84:87], v[160:163], v[176:179], v[84:87]
	v_mfma_f32_16x16x32_bf16 v[80:83], v[168:171], v[176:179], v[80:83]
	v_mfma_f32_16x16x32_bf16 v[76:79], v[160:163], v[184:187], v[76:79]
	v_mfma_f32_16x16x32_bf16 v[72:75], v[168:171], v[184:187], v[72:75]
	v_mfma_f32_16x16x32_bf16 v[48:51], v[160:163], v[192:195], v[48:51]
	v_mfma_f32_16x16x32_bf16 v[16:19], v[168:171], v[192:195], v[16:19]
	v_mfma_f32_16x16x32_bf16 v[40:43], v[160:163], v[200:203], v[40:43]
	v_mfma_f32_16x16x32_bf16 v[8:11], v[168:171], v[200:203], v[8:11]
	v_mfma_f32_16x16x32_bf16 v[84:87], v[164:167], v[180:183], v[84:87]
	v_mfma_f32_16x16x32_bf16 v[80:83], v[172:175], v[180:183], v[80:83]
	v_mfma_f32_16x16x32_bf16 v[76:79], v[164:167], v[188:191], v[76:79]
	v_mfma_f32_16x16x32_bf16 v[72:75], v[172:175], v[188:191], v[72:75]
	v_mfma_f32_16x16x32_bf16 v[48:51], v[164:167], v[196:199], v[48:51]
	v_mfma_f32_16x16x32_bf16 v[16:19], v[172:175], v[196:199], v[16:19]
	v_mfma_f32_16x16x32_bf16 v[40:43], v[164:167], v[204:207], v[40:43]
	v_mfma_f32_16x16x32_bf16 v[8:11], v[172:175], v[204:207], v[8:11]
	s_setprio 0
	s_barrier
	s_add_i32 s26, s88, s70
	v_lshl_add_u64 v[208:209], s[66:67], 0, v[138:139]
	s_mov_b32 m0, s26
	ds_read_b128 v[176:179], v240 offset:16384
	ds_read_b128 v[180:183], v240 offset:17408
	ds_read_b128 v[184:187], v240 offset:18432
	ds_read_b128 v[188:191], v240 offset:19456
	ds_read_b128 v[192:195], v240 offset:20480
	ds_read_b128 v[196:199], v240 offset:21504
	ds_read_b128 v[200:203], v240 offset:22528
	ds_read_b128 v[204:207], v240 offset:23552
	global_load_lds_dwordx4 v[208:209], off
	s_add_i32 m0, s26, 0x2000
	s_add_u32 s26, s66, 0x40000
	v_lshl_add_u64 v[210:211], s[66:67], 0, v[142:143]
	s_addc_u32 s27, s67, 0
	s_add_i32 s62, s89, s70
	global_load_lds_dwordx4 v[210:211], off
	v_lshl_add_u64 v[212:213], s[26:27], 0, v[138:139]
	s_mov_b32 m0, s62
	v_lshl_add_u64 v[214:215], s[68:69], 0, v[140:141]
	global_load_lds_dwordx4 v[212:213], off
	v_lshl_add_u64 v[212:213], s[26:27], 0, v[142:143]
	s_add_i32 m0, s62, 0x2000
	s_nop 0
	global_load_lds_dwordx4 v[212:213], off
	v_lshl_add_u64 v[212:213], s[68:69], 0, v[136:137]
	s_mov_b32 m0, s71
	s_nop 0
	global_load_lds_dwordx4 v[212:213], off
	s_mov_b32 m0, s72
	s_nop 0
	global_load_lds_dwordx4 v[214:215], off
	s_waitcnt vmcnt(8)
	ds_write_b64 v241, v[226:227]
	s_waitcnt lgkmcnt(0)
	s_barrier
	s_setprio 1
	s_waitcnt lgkmcnt(0)
	v_mfma_f32_16x16x32_bf16 v[52:55], v[64:67], v[176:179], v[52:55]
	v_mfma_f32_16x16x32_bf16 v[20:23], v[152:155], v[176:179], v[20:23]
	v_mfma_f32_16x16x32_bf16 v[44:47], v[64:67], v[184:187], v[44:47]
	v_mfma_f32_16x16x32_bf16 v[12:15], v[152:155], v[184:187], v[12:15]
	v_mfma_f32_16x16x32_bf16 v[132:135], v[64:67], v[192:195], v[132:135]
	v_mfma_f32_16x16x32_bf16 v[128:131], v[152:155], v[192:195], v[128:131]
	v_mfma_f32_16x16x32_bf16 v[64:67], v[64:67], v[200:203], v[124:127]
	v_mfma_f32_16x16x32_bf16 v[52:55], v[68:71], v[180:183], v[52:55]
	v_mfma_f32_16x16x32_bf16 v[20:23], v[156:159], v[180:183], v[20:23]
	v_mfma_f32_16x16x32_bf16 v[44:47], v[68:71], v[188:191], v[44:47]
	v_mfma_f32_16x16x32_bf16 v[12:15], v[156:159], v[188:191], v[12:15]
	v_mfma_f32_16x16x32_bf16 v[132:135], v[68:71], v[196:199], v[132:135]
	v_mfma_f32_16x16x32_bf16 v[128:131], v[156:159], v[196:199], v[128:131]
	v_mfma_f32_16x16x32_bf16 v[64:67], v[68:71], v[204:207], v[64:67]
	v_mfma_f32_16x16x32_bf16 v[68:71], v[152:155], v[200:203], v[120:123]
	v_mfma_f32_16x16x32_bf16 v[68:71], v[156:159], v[204:207], v[68:71]
	s_setprio 0
	s_setprio 1
	v_mfma_f32_16x16x32_bf16 v[36:39], v[160:163], v[176:179], v[36:39]
	v_mfma_f32_16x16x32_bf16 v[4:7], v[168:171], v[176:179], v[4:7]
	v_mfma_f32_16x16x32_bf16 v[32:35], v[160:163], v[184:187], v[32:35]
	v_mfma_f32_16x16x32_bf16 v[0:3], v[168:171], v[184:187], v[0:3]
	v_mfma_f32_16x16x32_bf16 v[116:119], v[160:163], v[192:195], v[116:119]
	v_mfma_f32_16x16x32_bf16 v[112:115], v[168:171], v[192:195], v[112:115]
	v_mfma_f32_16x16x32_bf16 v[108:111], v[160:163], v[200:203], v[108:111]
	v_mfma_f32_16x16x32_bf16 v[100:103], v[168:171], v[200:203], v[100:103]
	v_mfma_f32_16x16x32_bf16 v[36:39], v[164:167], v[180:183], v[36:39]
	v_mfma_f32_16x16x32_bf16 v[4:7], v[172:175], v[180:183], v[4:7]
	v_mfma_f32_16x16x32_bf16 v[32:35], v[164:167], v[188:191], v[32:35]
	v_mfma_f32_16x16x32_bf16 v[0:3], v[172:175], v[188:191], v[0:3]
	v_mfma_f32_16x16x32_bf16 v[116:119], v[164:167], v[196:199], v[116:119]
	v_mfma_f32_16x16x32_bf16 v[112:115], v[172:175], v[196:199], v[112:115]
	v_mfma_f32_16x16x32_bf16 v[108:111], v[164:167], v[204:207], v[108:111]
	v_mfma_f32_16x16x32_bf16 v[100:103], v[172:175], v[204:207], v[100:103]
	s_setprio 0
	s_barrier
	s_add_i32 s62, 0, 0x18000
	s_add_i32 s63, 0, 0x1c000
	v_add_u32_e32 v156, s62, v235
	v_add_u32_e32 v172, s63, v235
	ds_read_b128 v[120:123], v156
	ds_read_b128 v[124:127], v156 offset:1024
	ds_read_b128 v[152:155], v156 offset:2048
	ds_read_b128 v[156:159], v156 offset:3072
	ds_read_b128 v[160:163], v172
	ds_read_b128 v[164:167], v172 offset:1024
	ds_read_b128 v[168:171], v172 offset:2048
	ds_read_b128 v[172:175], v172 offset:3072
	s_add_u32 s26, s68, 0x2000
	s_addc_u32 s27, s69, 0
	s_mov_b32 m0, s73
	v_lshl_add_u64 v[216:217], s[26:27], 0, v[136:137]
	ds_read_b128 v[176:179], v240 offset:32768
	ds_read_b128 v[180:183], v240 offset:33792
	ds_read_b128 v[184:187], v240 offset:34816
	ds_read_b128 v[188:191], v240 offset:35840
	ds_read_b128 v[192:195], v240 offset:36864
	ds_read_b128 v[196:199], v240 offset:37888
	ds_read_b128 v[200:203], v240 offset:38912
	ds_read_b128 v[204:207], v240 offset:39936
	global_load_lds_dwordx4 v[216:217], off
	v_lshl_add_u64 v[216:217], s[26:27], 0, v[140:141]
	s_mov_b32 m0, s74
	s_nop 0
	global_load_lds_dwordx4 v[216:217], off
	s_waitcnt vmcnt(8)
	s_waitcnt lgkmcnt(0)
	s_barrier
	s_setprio 1
	s_waitcnt lgkmcnt(0)
	v_mfma_f32_16x16x32_bf16 v[104:107], v[120:123], v[176:179], v[104:107]
	v_mfma_f32_16x16x32_bf16 v[96:99], v[152:155], v[176:179], v[96:99]
	v_mfma_f32_16x16x32_bf16 v[92:95], v[120:123], v[184:187], v[92:95]
	v_mfma_f32_16x16x32_bf16 v[88:91], v[152:155], v[184:187], v[88:91]
	v_mfma_f32_16x16x32_bf16 v[60:63], v[120:123], v[192:195], v[60:63]
	v_mfma_f32_16x16x32_bf16 v[28:31], v[152:155], v[192:195], v[28:31]
	v_mfma_f32_16x16x32_bf16 v[56:59], v[120:123], v[200:203], v[56:59]
	v_mfma_f32_16x16x32_bf16 v[24:27], v[152:155], v[200:203], v[24:27]
	v_mfma_f32_16x16x32_bf16 v[104:107], v[124:127], v[180:183], v[104:107]
	v_mfma_f32_16x16x32_bf16 v[96:99], v[156:159], v[180:183], v[96:99]
	v_mfma_f32_16x16x32_bf16 v[92:95], v[124:127], v[188:191], v[92:95]
	v_mfma_f32_16x16x32_bf16 v[88:91], v[156:159], v[188:191], v[88:91]
	v_mfma_f32_16x16x32_bf16 v[60:63], v[124:127], v[196:199], v[60:63]
	v_mfma_f32_16x16x32_bf16 v[28:31], v[156:159], v[196:199], v[28:31]
	v_mfma_f32_16x16x32_bf16 v[56:59], v[124:127], v[204:207], v[56:59]
	v_mfma_f32_16x16x32_bf16 v[24:27], v[156:159], v[204:207], v[24:27]
	s_setprio 0
	s_setprio 1
	v_mfma_f32_16x16x32_bf16 v[84:87], v[160:163], v[176:179], v[84:87]
	v_mfma_f32_16x16x32_bf16 v[80:83], v[168:171], v[176:179], v[80:83]
	v_mfma_f32_16x16x32_bf16 v[76:79], v[160:163], v[184:187], v[76:79]
	v_mfma_f32_16x16x32_bf16 v[72:75], v[168:171], v[184:187], v[72:75]
	v_mfma_f32_16x16x32_bf16 v[48:51], v[160:163], v[192:195], v[48:51]
	v_mfma_f32_16x16x32_bf16 v[16:19], v[168:171], v[192:195], v[16:19]
	v_mfma_f32_16x16x32_bf16 v[40:43], v[160:163], v[200:203], v[40:43]
	v_mfma_f32_16x16x32_bf16 v[8:11], v[168:171], v[200:203], v[8:11]
	v_mfma_f32_16x16x32_bf16 v[84:87], v[164:167], v[180:183], v[84:87]
	v_mfma_f32_16x16x32_bf16 v[80:83], v[172:175], v[180:183], v[80:83]
	v_mfma_f32_16x16x32_bf16 v[76:79], v[164:167], v[188:191], v[76:79]
	v_mfma_f32_16x16x32_bf16 v[72:75], v[172:175], v[188:191], v[72:75]
	v_mfma_f32_16x16x32_bf16 v[48:51], v[164:167], v[196:199], v[48:51]
	v_mfma_f32_16x16x32_bf16 v[16:19], v[172:175], v[196:199], v[16:19]
	v_mfma_f32_16x16x32_bf16 v[40:43], v[164:167], v[204:207], v[40:43]
	v_mfma_f32_16x16x32_bf16 v[8:11], v[172:175], v[204:207], v[8:11]
	s_setprio 0
	s_barrier
	s_add_i32 s26, s62, s70
	v_lshl_add_u64 v[208:209], v[208:209], 0, s[10:11]
	s_mov_b32 m0, s26
	ds_read_b128 v[176:179], v240 offset:49152
	ds_read_b128 v[180:183], v240 offset:50176
	ds_read_b128 v[184:187], v240 offset:51200
	ds_read_b128 v[188:191], v240 offset:52224
	ds_read_b128 v[192:195], v240 offset:53248
	ds_read_b128 v[196:199], v240 offset:54272
	ds_read_b128 v[200:203], v240 offset:55296
	ds_read_b128 v[204:207], v240 offset:56320
	global_load_lds_dwordx4 v[208:209], off
	s_add_i32 m0, s26, 0x2000
	s_add_u32 s26, s66, 0x40080
	v_lshl_add_u64 v[208:209], v[210:211], 0, s[10:11]
	s_addc_u32 s27, s67, 0
	s_add_i32 s62, s63, s70
	global_load_lds_dwordx4 v[208:209], off
	v_lshl_add_u64 v[208:209], s[26:27], 0, v[138:139]
	s_mov_b32 m0, s62
	s_nop 0
	global_load_lds_dwordx4 v[208:209], off
	v_lshl_add_u64 v[208:209], s[26:27], 0, v[142:143]
	s_add_i32 m0, s62, 0x2000
	s_nop 0
	global_load_lds_dwordx4 v[208:209], off
	v_lshl_add_u64 v[208:209], v[212:213], 0, s[10:11]
	s_mov_b32 m0, s78
	s_nop 0
	global_load_lds_dwordx4 v[208:209], off
	v_lshl_add_u64 v[208:209], v[214:215], 0, s[10:11]
	s_mov_b32 m0, s79
	s_nop 0
	global_load_lds_dwordx4 v[208:209], off
	s_waitcnt vmcnt(8)
	s_waitcnt lgkmcnt(0)
	s_barrier
	s_setprio 1
	s_waitcnt lgkmcnt(0)
	v_mfma_f32_16x16x32_bf16 v[52:55], v[120:123], v[176:179], v[52:55]
	v_mfma_f32_16x16x32_bf16 v[44:47], v[120:123], v[184:187], v[44:47]
	v_mfma_f32_16x16x32_bf16 v[132:135], v[120:123], v[192:195], v[132:135]
	v_mfma_f32_16x16x32_bf16 v[64:67], v[120:123], v[200:203], v[64:67]
	v_mfma_f32_16x16x32_bf16 v[52:55], v[124:127], v[180:183], v[52:55]
	v_mfma_f32_16x16x32_bf16 v[20:23], v[152:155], v[176:179], v[20:23]
	v_mfma_f32_16x16x32_bf16 v[44:47], v[124:127], v[188:191], v[44:47]
	v_mfma_f32_16x16x32_bf16 v[12:15], v[152:155], v[184:187], v[12:15]
	v_mfma_f32_16x16x32_bf16 v[132:135], v[124:127], v[196:199], v[132:135]
	v_mfma_f32_16x16x32_bf16 v[128:131], v[152:155], v[192:195], v[128:131]
	v_mfma_f32_16x16x32_bf16 v[124:127], v[124:127], v[204:207], v[64:67]
	v_mfma_f32_16x16x32_bf16 v[64:67], v[152:155], v[200:203], v[68:71]
	v_mfma_f32_16x16x32_bf16 v[20:23], v[156:159], v[180:183], v[20:23]
	v_mfma_f32_16x16x32_bf16 v[12:15], v[156:159], v[188:191], v[12:15]
	v_mfma_f32_16x16x32_bf16 v[128:131], v[156:159], v[196:199], v[128:131]
	v_mfma_f32_16x16x32_bf16 v[120:123], v[156:159], v[204:207], v[64:67]
	s_setprio 0
	s_setprio 1
	v_mfma_f32_16x16x32_bf16 v[64:67], v[160:163], v[192:195], v[116:119]
	v_mfma_f32_16x16x32_bf16 v[116:119], v[164:167], v[196:199], v[64:67]
	v_mfma_f32_16x16x32_bf16 v[64:67], v[168:171], v[192:195], v[112:115]
	v_mfma_f32_16x16x32_bf16 v[112:115], v[172:175], v[196:199], v[64:67]
	v_mfma_f32_16x16x32_bf16 v[64:67], v[160:163], v[200:203], v[108:111]
	v_mfma_f32_16x16x32_bf16 v[36:39], v[160:163], v[176:179], v[36:39]
	v_mfma_f32_16x16x32_bf16 v[4:7], v[168:171], v[176:179], v[4:7]
	v_mfma_f32_16x16x32_bf16 v[32:35], v[160:163], v[184:187], v[32:35]
	v_mfma_f32_16x16x32_bf16 v[0:3], v[168:171], v[184:187], v[0:3]
	v_mfma_f32_16x16x32_bf16 v[108:111], v[164:167], v[204:207], v[64:67]
	v_mfma_f32_16x16x32_bf16 v[64:67], v[168:171], v[200:203], v[100:103]
	v_mfma_f32_16x16x32_bf16 v[36:39], v[164:167], v[180:183], v[36:39]
	v_mfma_f32_16x16x32_bf16 v[4:7], v[172:175], v[180:183], v[4:7]
	v_mfma_f32_16x16x32_bf16 v[32:35], v[164:167], v[188:191], v[32:35]
	v_mfma_f32_16x16x32_bf16 v[0:3], v[172:175], v[188:191], v[0:3]
	v_mfma_f32_16x16x32_bf16 v[100:103], v[172:175], v[204:207], v[64:67]
	s_setprio 0
	s_barrier
	s_add_i32 s96, s96, 2
	s_add_u32 s94, s94, 0x100
	s_addc_u32 s95, s95, 0
	s_cmp_gt_u32 s96, 13
	s_mov_b64 s[62:63], s[64:65]
	s_cbranch_scc0 .LBB0_882
	s_and_b64 vcc, exec, s[18:19]
	s_cbranch_vccz .LBB0_885
	s_barrier
.LBB0_885:
	v_lshl_add_u32 v152, s58, 8, v236
	v_ashrrev_i32_e32 v153, 31, v152
	v_mov_b32_e32 v64, v218
	v_mov_b32_e32 v65, v219
	v_mov_b32_e32 v66, v220
	v_mov_b32_e32 v67, v221
	v_mov_b32_e32 v68, v222
	v_mov_b32_e32 v69, v223
	v_mov_b32_e32 v70, v224
	v_mov_b32_e32 v71, v225
	v_lshl_or_b32 v154, s60, 7, v237
	v_cmp_lt_i32_e32 vcc, 14, v234
	s_mov_b64 s[60:61], 0
	v_ashrrev_i32_e32 v155, 31, v154
	v_pk_mul_f32 v[204:205], v[134:135], v[70:71] op_sel_hi:[1,0]
	v_pk_mul_f32 v[206:207], v[132:133], v[70:71] op_sel_hi:[1,0]
	v_pk_mul_f32 v[172:173], v[130:131], v[70:71] op_sel_hi:[1,0]
	v_pk_mul_f32 v[174:175], v[128:129], v[70:71] op_sel_hi:[1,0]
	v_pk_mul_f32 v[202:203], v[118:119], v[70:71] op_sel_hi:[1,0]
	v_pk_mul_f32 v[200:201], v[116:117], v[70:71] op_sel_hi:[1,0]
	v_pk_mul_f32 v[170:171], v[114:115], v[70:71] op_sel_hi:[1,0]
	v_pk_mul_f32 v[168:169], v[112:113], v[70:71] op_sel_hi:[1,0]
	v_mov_b32_e32 v70, v71
	v_pk_mul_f32 v[212:213], v[126:127], v[70:71] op_sel_hi:[1,0]
	v_pk_mul_f32 v[214:215], v[124:125], v[70:71] op_sel_hi:[1,0]
	v_pk_mul_f32 v[180:181], v[122:123], v[70:71] op_sel_hi:[1,0]
	v_pk_mul_f32 v[182:183], v[120:121], v[70:71] op_sel_hi:[1,0]
	v_pk_mul_f32 v[208:209], v[110:111], v[70:71] op_sel_hi:[1,0]
	v_pk_mul_f32 v[210:211], v[108:109], v[70:71] op_sel_hi:[1,0]
	v_pk_mul_f32 v[176:177], v[102:103], v[70:71] op_sel_hi:[1,0]
	v_pk_mul_f32 v[178:179], v[100:101], v[70:71] op_sel_hi:[1,0]
	s_and_saveexec_b64 s[26:27], vcc
	s_xor_b64 s[62:63], exec, s[26:27]
	s_cbranch_execz .LBB0_887
	s_ashr_i32 s59, s58, 31
	s_lshl_b64 s[26:27], s[58:59], 3
	s_add_u32 s26, s26, s81
	s_addc_u32 s27, s27, s82
	s_mulk_i32 s27, 0x2c00
	s_mul_hi_u32 s51, s26, 0x2c00
	s_add_i32 s51, s51, s27
	s_mulk_i32 s26, 0x2c00
	s_add_u32 s26, s14, s26
	s_addc_u32 s27, s15, s51
	v_lshl_add_u64 v[108:109], v[154:155], 1, s[26:27]
	v_add_co_u32_e32 v110, vcc, s90, v108
	v_cvt_pk_bf16_f32 v100, v206, v207
	v_cvt_pk_bf16_f32 v101, v204, v205
	v_cvt_pk_bf16_f32 v102, v174, v175
	v_cvt_pk_bf16_f32 v103, v172, v173
	s_nop 1
	v_addc_co_u32_e32 v111, vcc, 0, v109, vcc
	global_store_dwordx4 v[110:111], v[100:103], off offset:2048
	v_add_co_u32_e32 v110, vcc, s77, v108
	v_lshl_add_u64 v[70:71], v[108:109], 0, s[44:45]
	s_nop 0
	v_addc_co_u32_e32 v111, vcc, 0, v109, vcc
	v_cvt_pk_bf16_f32 v100, v200, v201
	v_cvt_pk_bf16_f32 v101, v202, v203
	v_cvt_pk_bf16_f32 v102, v168, v169
	v_cvt_pk_bf16_f32 v103, v170, v171
	v_add_co_u32_e32 v108, vcc, s80, v108
	global_store_dwordx4 v[110:111], v[100:103], off offset:3584
	s_nop 0
	v_addc_co_u32_e32 v109, vcc, 0, v109, vcc
	v_cvt_pk_bf16_f32 v100, v214, v215
	v_cvt_pk_bf16_f32 v101, v212, v213
	v_cvt_pk_bf16_f32 v102, v182, v183
	v_cvt_pk_bf16_f32 v103, v180, v181
	s_mov_b64 s[60:61], exec
	global_store_dwordx4 v[108:109], v[100:103], off offset:1024
	s_nop 1
	v_cvt_pk_bf16_f32 v100, v210, v211
	v_cvt_pk_bf16_f32 v101, v208, v209
	v_cvt_pk_bf16_f32 v102, v178, v179
	v_cvt_pk_bf16_f32 v103, v176, v177

.LBB0_893:
	s_or_b64 exec, exec, s[58:59]
	v_lshlrev_b32_e32 v232, 2, v237
	v_mov_b32_e32 v233, 0
	v_add_u32_e32 v232, 0x22c00, v232
	ds_read_b128 v[106:109], v232 offset:512
	ds_read_b128 v[114:117], v232 offset:1024
	ds_read_b128 v[110:113], v232 offset:1536
	ds_read_b128 v[118:121], v232 offset:2048
	ds_read_b128 v[122:125], v232 offset:2560
	ds_read_b128 v[126:129], v232 offset:3584
	ds_read_b128 v[130:133], v232 offset:3072
	ds_read_b128 v[102:105], v232 offset:0
	v_mov_b32_dpp v222, v206 row_shr:1 row_mask:0xf bank_mask:0xf bound_ctrl:1
	v_mov_b32_dpp v226, v214 row_shr:1 row_mask:0xf bank_mask:0xf bound_ctrl:1
	v_mov_b32_dpp v216, v200 row_shr:1 row_mask:0xf bank_mask:0xf bound_ctrl:1
	v_mov_b32_dpp v218, v210 row_shr:1 row_mask:0xf bank_mask:0xf bound_ctrl:1
	v_mov_b32_dpp v223, v207 row_shr:1 row_mask:0xf bank_mask:0xf bound_ctrl:1
	v_mov_b32_dpp v227, v215 row_shr:1 row_mask:0xf bank_mask:0xf bound_ctrl:1
	v_mov_b32_dpp v217, v201 row_shr:1 row_mask:0xf bank_mask:0xf bound_ctrl:1
	v_mov_b32_dpp v219, v211 row_shr:1 row_mask:0xf bank_mask:0xf bound_ctrl:1
	v_mov_b32_dpp v228, v204 row_shr:1 row_mask:0xf bank_mask:0xf bound_ctrl:1
	v_mov_b32_dpp v230, v212 row_shr:1 row_mask:0xf bank_mask:0xf bound_ctrl:1
	v_mov_b32_dpp v220, v202 row_shr:1 row_mask:0xf bank_mask:0xf bound_ctrl:1
	v_mov_b32_dpp v224, v208 row_shr:1 row_mask:0xf bank_mask:0xf bound_ctrl:1
	v_mov_b32_dpp v229, v205 row_shr:1 row_mask:0xf bank_mask:0xf bound_ctrl:1
	v_mov_b32_dpp v231, v213 row_shr:1 row_mask:0xf bank_mask:0xf bound_ctrl:1
	v_mov_b32_dpp v221, v203 row_shr:1 row_mask:0xf bank_mask:0xf bound_ctrl:1
	v_mov_b32_dpp v225, v209 row_shr:1 row_mask:0xf bank_mask:0xf bound_ctrl:1
	s_waitcnt lgkmcnt(4)
	ds_read_b128 v[82:85], v232 offset:1040
	ds_read_b128 v[86:89], v232 offset:2064
	ds_read_b128 v[90:93], v232 offset:2576
	ds_read_b128 v[94:97], v232 offset:3600
	ds_read_b128 v[78:81], v232 offset:1552
	ds_read_b128 v[74:77], v232 offset:528
	ds_read_b128 v[70:73], v232 offset:16
	ds_read_b128 v[98:101], v232 offset:3088
	v_pk_mul_f32 v[46:47], v[46:47], v[68:69] op_sel:[0,1]
	v_pk_mul_f32 v[252:253], v[32:33], v[68:69] op_sel:[0,1]
	s_waitcnt lgkmcnt(0)
	v_pk_mul_f32 v[32:33], v[204:205], v[108:109]
	v_mov_b32_e32 v232, v67
	v_pk_fma_f32 v[32:33], v[46:47], v[104:105], v[32:33]
	v_pk_mul_f32 v[244:245], v[54:55], v[68:69] op_sel_hi:[1,0]
	v_pk_fma_f32 v[32:33], v[212:213], v[116:117], v[32:33]
	v_pk_mul_f32 v[54:55], v[48:49], v[66:67] op_sel_hi:[1,0]
	v_pk_add_f32 v[32:33], v[32:33], v[112:113]
	v_pk_mul_f32 v[48:49], v[42:43], v[232:233] op_sel_hi:[1,0]
	v_mul_f32_e32 v42, 0xbfb8aa3b, v32
	v_mul_f32_e32 v43, 0xbfb8aa3b, v33
	v_exp_f32_e32 v42, v42
	v_exp_f32_e32 v43, v43
	v_pk_mul_f32 v[44:45], v[44:45], v[68:69] op_sel:[0,1]
	v_pk_mul_f32 v[250:251], v[34:35], v[68:69] op_sel:[0,1]
	v_pk_mul_f32 v[34:35], v[206:207], v[106:107]
	v_add_f32_e32 v42, 1.0, v42
	v_pk_fma_f32 v[34:35], v[44:45], v[102:103], v[34:35]
	v_add_f32_e32 v43, 1.0, v43
	v_pk_fma_f32 v[34:35], v[214:215], v[114:115], v[34:35]
	v_pk_mul_f32 v[242:243], v[52:53], v[68:69] op_sel_hi:[1,0]
	v_pk_add_f32 v[34:35], v[34:35], v[110:111]
	v_pk_mul_f32 v[52:53], v[50:51], v[66:67] op_sel_hi:[1,0]
	v_pk_mul_f32 v[50:51], v[40:41], v[232:233] op_sel_hi:[1,0]
	v_mul_f32_e32 v40, 0xbfb8aa3b, v34
	v_mul_f32_e32 v41, 0xbfb8aa3b, v35
	v_rcp_f32_e32 v42, v42
	v_rcp_f32_e32 v43, v43
	v_pk_mul_f32 v[248:249], v[36:37], v[68:69] op_sel_hi:[1,0]
	v_pk_mul_f32 v[36:37], v[202:203], v[124:125]
	v_exp_f32_e32 v40, v40
	v_exp_f32_e32 v41, v41
	v_pk_fma_f32 v[36:37], v[250:251], v[120:121], v[36:37]
	v_pk_mul_f32 v[32:33], v[32:33], v[42:43]
	v_pk_fma_f32 v[36:37], v[208:209], v[132:133], v[36:37]
	v_add_f32_e32 v40, 1.0, v40
	v_pk_add_f32 v[36:37], v[36:37], v[128:129]
	v_add_f32_e32 v41, 1.0, v41
	v_pk_mul_f32 v[32:33], v[32:33], v[36:37]
	v_pk_mul_f32 v[36:37], v[44:45], v[106:107]
	v_rcp_f32_e32 v40, v40
	v_rcp_f32_e32 v41, v41
	v_pk_fma_f32 v[36:37], v[242:243], v[102:103], v[36:37]
	v_pk_mul_f32 v[246:247], v[38:39], v[68:69] op_sel_hi:[1,0]
	v_pk_mul_f32 v[38:39], v[200:201], v[122:123]
	v_pk_fma_f32 v[36:37], v[206:207], v[114:115], v[36:37]
	v_pk_fma_f32 v[38:39], v[252:253], v[118:119], v[38:39]
	v_pk_add_f32 v[36:37], v[36:37], v[110:111]
	v_pk_mul_f32 v[62:63], v[62:63], v[66:67] op_sel_hi:[1,0]
	v_pk_mul_f32 v[60:61], v[60:61], v[66:67] op_sel_hi:[1,0]
	v_pk_fma_f32 v[38:39], v[210:211], v[130:131], v[38:39]
	v_mul_f32_e32 v67, 0xbfb8aa3b, v36
	v_pk_add_f32 v[38:39], v[38:39], v[126:127]
	v_pk_mul_f32 v[34:35], v[34:35], v[40:41]
	v_exp_f32_e32 v67, v67
	v_mul_f32_e32 v153, 0xbfb8aa3b, v37
	v_pk_mul_f32 v[34:35], v[34:35], v[38:39]
	v_pk_mul_f32 v[38:39], v[46:47], v[108:109]
	v_exp_f32_e32 v153, v153
	v_pk_fma_f32 v[38:39], v[244:245], v[104:105], v[38:39]
	v_pk_mul_f32 v[42:43], v[252:253], v[122:123]
	v_pk_fma_f32 v[38:39], v[204:205], v[116:117], v[38:39]
	v_pk_fma_f32 v[42:43], v[248:249], v[118:119], v[42:43]
	v_pk_add_f32 v[38:39], v[38:39], v[112:113]
	v_add_f32_e32 v67, 1.0, v67
	v_pk_mul_f32 v[40:41], v[250:251], v[124:125]
	v_pk_fma_f32 v[42:43], v[200:201], v[130:131], v[42:43]
	v_rcp_f32_e32 v200, v67
	v_add_f32_e32 v67, 1.0, v153
	v_mul_f32_e32 v153, 0xbfb8aa3b, v38
	v_pk_fma_f32 v[40:41], v[246:247], v[120:121], v[40:41]
	v_exp_f32_e32 v153, v153
	v_mul_f32_e32 v201, 0xbfb8aa3b, v39
	v_pk_fma_f32 v[40:41], v[202:203], v[132:133], v[40:41]
	v_exp_f32_e32 v203, v201
	v_rcp_f32_e32 v201, v67
	v_add_f32_e32 v67, 1.0, v153
	v_rcp_f32_e32 v202, v67
	v_add_f32_e32 v67, 1.0, v203
	v_rcp_f32_e32 v203, v67
	v_pk_add_f32 v[40:41], v[40:41], v[128:129]
	v_pk_mul_f32 v[200:201], v[36:37], v[200:201]
	v_pk_mul_f32 v[56:57], v[56:57], v[232:233] op_sel_hi:[1,0]
	v_pk_mul_f32 v[36:37], v[38:39], v[202:203]
	v_pk_add_f32 v[42:43], v[42:43], v[126:127]
	v_pk_mul_f32 v[36:37], v[36:37], v[40:41]
	v_pk_mul_f32 v[40:41], v[242:243], v[106:107]
	v_pk_mul_f32 v[58:59], v[58:59], v[232:233] op_sel_hi:[1,0]
	v_pk_fma_f32 v[40:41], v[56:57], v[102:103], v[40:41]
	v_pk_mul_f32 v[38:39], v[200:201], v[42:43]
	v_pk_fma_f32 v[40:41], v[44:45], v[114:115], v[40:41]
	v_pk_mul_f32 v[42:43], v[244:245], v[108:109]
	v_pk_add_f32 v[40:41], v[40:41], v[110:111]
	v_pk_fma_f32 v[42:43], v[58:59], v[104:105], v[42:43]
	v_mul_f32_e32 v67, 0xbfb8aa3b, v40
	v_exp_f32_e32 v67, v67
	v_pk_fma_f32 v[42:43], v[46:47], v[116:117], v[42:43]
	v_pk_mul_f32 v[44:45], v[248:249], v[122:123]
	v_pk_add_f32 v[42:43], v[42:43], v[112:113]
	v_add_f32_e32 v67, 1.0, v67
	v_mul_f32_e32 v153, 0xbfb8aa3b, v42
	v_rcp_f32_e32 v200, v67
	v_mul_f32_e32 v67, 0xbfb8aa3b, v41
	v_exp_f32_e32 v153, v153
	v_mul_f32_e32 v201, 0xbfb8aa3b, v43
	v_exp_f32_e32 v67, v67
	v_exp_f32_e32 v201, v201
	v_add_f32_e32 v153, 1.0, v153
	v_rcp_f32_e32 v202, v153
	v_add_f32_e32 v67, 1.0, v67
	v_add_f32_e32 v153, 1.0, v201
	v_rcp_f32_e32 v203, v153
	v_rcp_f32_e32 v201, v67
	v_pk_mul_f32 v[46:47], v[246:247], v[124:125]
	v_pk_fma_f32 v[44:45], v[50:51], v[118:119], v[44:45]
	v_pk_fma_f32 v[46:47], v[48:49], v[120:121], v[46:47]
	v_pk_fma_f32 v[44:45], v[252:253], v[130:131], v[44:45]
	v_pk_fma_f32 v[46:47], v[250:251], v[132:133], v[46:47]
	v_pk_add_f32 v[44:45], v[44:45], v[126:127]
	v_pk_add_f32 v[46:47], v[46:47], v[128:129]
	v_pk_mul_f32 v[42:43], v[42:43], v[202:203]
	v_pk_mul_f32 v[200:201], v[40:41], v[200:201]
	v_pk_mul_f32 v[40:41], v[42:43], v[46:47]
	v_pk_mul_f32 v[42:43], v[200:201], v[44:45]
	v_pk_mul_f32 v[44:45], v[56:57], v[106:107]
	v_pk_mul_f32 v[46:47], v[58:59], v[108:109]
	v_pk_fma_f32 v[44:45], v[60:61], v[102:103], v[44:45]
	v_pk_fma_f32 v[46:47], v[62:63], v[104:105], v[46:47]
	v_pk_fma_f32 v[44:45], v[242:243], v[114:115], v[44:45]
	v_pk_fma_f32 v[46:47], v[244:245], v[116:117], v[46:47]
	v_pk_add_f32 v[44:45], v[44:45], v[110:111]
	v_pk_add_f32 v[46:47], v[46:47], v[112:113]
	v_mul_f32_e32 v67, 0xbfb8aa3b, v44
	v_exp_f32_e32 v67, v67
	v_mul_f32_e32 v153, 0xbfb8aa3b, v46
	v_exp_f32_e32 v153, v153
	v_mul_f32_e32 v205, 0xbfb8aa3b, v47
	v_add_f32_e32 v67, 1.0, v67
	v_rcp_f32_e32 v204, v67
	v_mul_f32_e32 v67, 0xbfb8aa3b, v45
	v_exp_f32_e32 v205, v205
	v_exp_f32_e32 v67, v67
	v_add_f32_e32 v153, 1.0, v153
	v_rcp_f32_e32 v206, v153
	v_add_f32_e32 v153, 1.0, v205
	v_add_f32_e32 v67, 1.0, v67
	v_rcp_f32_e32 v207, v153
	v_pk_mul_f32 v[202:203], v[48:49], v[124:125]
	v_rcp_f32_e32 v205, v67
	v_pk_fma_f32 v[202:203], v[52:53], v[120:121], v[202:203]
	v_pk_mul_f32 v[46:47], v[46:47], v[206:207]
	v_pk_fma_f32 v[202:203], v[246:247], v[132:133], v[202:203]
	v_pk_mul_f32 v[204:205], v[44:45], v[204:205]
	v_pk_add_f32 v[202:203], v[202:203], v[128:129]
	v_pk_mul_f32 v[200:201], v[50:51], v[122:123]
	v_pk_mul_f32 v[44:45], v[46:47], v[202:203]
	v_pk_mul_f32 v[202:203], v[60:61], v[106:107]
	v_pk_fma_f32 v[200:201], v[54:55], v[118:119], v[200:201]
	v_pk_fma_f32 v[202:203], v[198:199], v[102:103], v[202:203]
	v_pk_fma_f32 v[200:201], v[248:249], v[130:131], v[200:201]
	v_pk_fma_f32 v[56:57], v[56:57], v[114:115], v[202:203]
	v_pk_add_f32 v[200:201], v[200:201], v[126:127]
	v_pk_add_f32 v[56:57], v[56:57], v[110:111]
	v_pk_mul_f32 v[46:47], v[204:205], v[200:201]
	v_mul_f32_e32 v67, 0xbfb8aa3b, v56
	v_exp_f32_e32 v67, v67
	v_pk_mul_f32 v[200:201], v[62:63], v[108:109]
	v_pk_mul_f32 v[202:203], v[54:55], v[122:123]
	v_pk_fma_f32 v[200:201], v[194:195], v[104:105], v[200:201]
	v_add_f32_e32 v67, 1.0, v67
	v_pk_fma_f32 v[58:59], v[58:59], v[116:117], v[200:201]
	v_pk_mul_f32 v[200:201], v[52:53], v[124:125]
	v_pk_add_f32 v[58:59], v[58:59], v[112:113]
	v_pk_fma_f32 v[200:201], v[196:197], v[120:121], v[200:201]
	v_mul_f32_e32 v153, 0xbfb8aa3b, v58
	v_pk_fma_f32 v[48:49], v[48:49], v[132:133], v[200:201]
	v_rcp_f32_e32 v200, v67
	v_mul_f32_e32 v67, 0xbfb8aa3b, v57
	v_exp_f32_e32 v67, v67
	v_exp_f32_e32 v153, v153
	v_mul_f32_e32 v201, 0xbfb8aa3b, v59
	v_exp_f32_e32 v201, v201
	v_pk_fma_f32 v[202:203], v[192:193], v[118:119], v[202:203]
	v_add_f32_e32 v67, 1.0, v67
	v_add_f32_e32 v153, 1.0, v153
	v_pk_fma_f32 v[50:51], v[50:51], v[130:131], v[202:203]
	v_rcp_f32_e32 v202, v153
	v_add_f32_e32 v153, 1.0, v201
	v_rcp_f32_e32 v201, v67
	v_pk_add_f32 v[50:51], v[50:51], v[126:127]
	v_rcp_f32_e32 v203, v153
	v_pk_add_f32 v[48:49], v[48:49], v[128:129]
	v_pk_mul_f32 v[56:57], v[56:57], v[200:201]
	s_andn2_b64 vcc, exec, s[6:7]
	v_pk_mul_f32 v[50:51], v[56:57], v[50:51]
	v_pk_mul_f32 v[56:57], v[194:195], v[108:109]
	v_pk_mul_f32 v[58:59], v[58:59], v[202:203]
	v_pk_fma_f32 v[56:57], v[186:187], v[104:105], v[56:57]
	v_pk_mul_f32 v[48:49], v[58:59], v[48:49]
	v_pk_fma_f32 v[56:57], v[62:63], v[116:117], v[56:57]
	v_pk_mul_f32 v[62:63], v[192:193], v[122:123]
	v_pk_add_f32 v[56:57], v[56:57], v[112:113]
	v_pk_fma_f32 v[62:63], v[184:185], v[118:119], v[62:63]
	v_pk_mul_f32 v[58:59], v[198:199], v[106:107]
	v_pk_fma_f32 v[54:55], v[54:55], v[130:131], v[62:63]
	v_mul_f32_e32 v62, 0xbfb8aa3b, v56
	v_mul_f32_e32 v63, 0xbfb8aa3b, v57
	v_exp_f32_e32 v62, v62
	v_exp_f32_e32 v63, v63
	v_pk_fma_f32 v[58:59], v[190:191], v[102:103], v[58:59]
	v_pk_add_f32 v[54:55], v[54:55], v[126:127]
	v_pk_fma_f32 v[58:59], v[60:61], v[114:115], v[58:59]
	v_pk_mul_f32 v[60:61], v[196:197], v[124:125]
	v_pk_add_f32 v[58:59], v[58:59], v[110:111]
	v_pk_fma_f32 v[60:61], v[188:189], v[120:121], v[60:61]
	v_add_f32_e32 v62, 1.0, v62
	v_add_f32_e32 v63, 1.0, v63
	v_mul_f32_e32 v67, 0xbfb8aa3b, v58
	v_pk_fma_f32 v[52:53], v[52:53], v[132:133], v[60:61]
	v_mul_f32_e32 v61, 0xbfb8aa3b, v59
	v_rcp_f32_e32 v62, v62
	v_rcp_f32_e32 v63, v63
	v_exp_f32_e32 v67, v67
	v_exp_f32_e32 v61, v61
	v_pk_add_f32 v[52:53], v[52:53], v[128:129]
	v_pk_mul_f32 v[56:57], v[56:57], v[62:63]
	v_add_f32_e32 v60, 1.0, v67
	v_add_f32_e32 v61, 1.0, v61
	v_pk_mul_f32 v[52:53], v[56:57], v[52:53]
	v_pk_mul_f32 v[56:57], v[102:103], v[226:227]
	v_rcp_f32_e32 v60, v60
	v_rcp_f32_e32 v61, v61
	v_pk_fma_f32 v[56:57], v[190:191], v[106:107], v[56:57]
	v_pk_mul_f32 v[62:63], v[118:119], v[218:219]
	v_pk_fma_f32 v[56:57], v[198:199], v[114:115], v[56:57]
	v_pk_mul_f32 v[58:59], v[58:59], v[60:61]
	v_pk_add_f32 v[56:57], v[110:111], v[56:57]
	v_pk_mul_f32 v[54:55], v[58:59], v[54:55]
	v_mul_f32_e32 v67, 0xbfb8aa3b, v56
	v_exp_f32_e32 v67, v67
	v_mul_f32_e32 v153, 0xbfb8aa3b, v57
	v_pk_mul_f32 v[58:59], v[104:105], v[230:231]
	v_exp_f32_e32 v153, v153
	v_pk_fma_f32 v[58:59], v[186:187], v[108:109], v[58:59]
	v_pk_fma_f32 v[62:63], v[184:185], v[122:123], v[62:63]
	v_pk_fma_f32 v[58:59], v[194:195], v[116:117], v[58:59]
	v_add_f32_e32 v67, 1.0, v67
	v_pk_add_f32 v[58:59], v[112:113], v[58:59]
	v_pk_fma_f32 v[62:63], v[192:193], v[130:131], v[62:63]
	v_rcp_f32_e32 v192, v67
	v_add_f32_e32 v67, 1.0, v153
	v_mul_f32_e32 v153, 0xbfb8aa3b, v58
	v_exp_f32_e32 v153, v153
	v_mul_f32_e32 v193, 0xbfb8aa3b, v59
	v_exp_f32_e32 v195, v193
	v_rcp_f32_e32 v193, v67
	v_add_f32_e32 v67, 1.0, v153
	v_rcp_f32_e32 v194, v67
	v_add_f32_e32 v67, 1.0, v195
	v_rcp_f32_e32 v195, v67
	v_pk_mul_f32 v[60:61], v[120:121], v[224:225]
	v_pk_mul_f32 v[192:193], v[56:57], v[192:193]
	v_pk_fma_f32 v[60:61], v[188:189], v[124:125], v[60:61]
	v_pk_mul_f32 v[56:57], v[58:59], v[194:195]
	v_pk_fma_f32 v[60:61], v[196:197], v[132:133], v[60:61]
	v_pk_add_f32 v[62:63], v[126:127], v[62:63]
	v_pk_add_f32 v[60:61], v[128:129], v[60:61]
	v_pk_mul_f32 v[58:59], v[62:63], v[192:193]
	v_pk_mul_f32 v[56:57], v[60:61], v[56:57]
	v_pk_mul_f32 v[60:61], v[106:107], v[226:227]
	v_pk_mul_f32 v[62:63], v[108:109], v[230:231]
	v_pk_fma_f32 v[60:61], v[102:103], v[222:223], v[60:61]
	v_pk_fma_f32 v[62:63], v[104:105], v[228:229], v[62:63]
	v_pk_fma_f32 v[60:61], v[190:191], v[114:115], v[60:61]
	v_pk_mul_f32 v[104:105], v[122:123], v[218:219]
	v_pk_add_f32 v[60:61], v[110:111], v[60:61]
	v_pk_fma_f32 v[104:105], v[118:119], v[216:217], v[104:105]
	v_mul_f32_e32 v67, 0xbfb8aa3b, v60
	v_pk_mul_f32 v[102:103], v[124:125], v[224:225]
	v_exp_f32_e32 v67, v67
	v_mul_f32_e32 v106, 0xbfb8aa3b, v61
	v_pk_fma_f32 v[104:105], v[184:185], v[130:131], v[104:105]
	v_pk_fma_f32 v[102:103], v[120:121], v[220:221], v[102:103]
	v_exp_f32_e32 v107, v106
	v_pk_add_f32 v[104:105], v[126:127], v[104:105]
	v_pk_mul_f32 v[120:121], v[14:15], v[68:69] op_sel:[0,1]
	v_pk_mul_f32 v[126:127], v[0:1], v[68:69] op_sel:[0,1]
	v_pk_mul_f32 v[0:1], v[172:173], v[76:77]
	v_pk_mul_f32 v[122:123], v[12:13], v[68:69] op_sel:[0,1]
	v_pk_mul_f32 v[124:125], v[2:3], v[68:69] op_sel:[0,1]
	v_pk_mul_f32 v[2:3], v[174:175], v[74:75]
	v_pk_fma_f32 v[0:1], v[120:121], v[72:73], v[0:1]
	v_pk_fma_f32 v[62:63], v[186:187], v[116:117], v[62:63]
	v_pk_fma_f32 v[2:3], v[122:123], v[70:71], v[2:3]
	v_pk_fma_f32 v[0:1], v[180:181], v[84:85], v[0:1]
	v_pk_add_f32 v[62:63], v[112:113], v[62:63]
	v_add_f32_e32 v67, 1.0, v67
	v_pk_fma_f32 v[2:3], v[182:183], v[82:83], v[2:3]
	v_pk_add_f32 v[0:1], v[0:1], v[80:81]
	v_rcp_f32_e32 v106, v67
	v_add_f32_e32 v67, 1.0, v107
	v_mul_f32_e32 v107, 0xbfb8aa3b, v62
	v_pk_mul_f32 v[110:111], v[26:27], v[232:233] op_sel_hi:[1,0]
	v_pk_add_f32 v[2:3], v[2:3], v[78:79]
	v_mul_f32_e32 v26, 0xbfb8aa3b, v0
	v_mul_f32_e32 v27, 0xbfb8aa3b, v1
	v_exp_f32_e32 v108, v107
	v_mul_f32_e32 v107, 0xbfb8aa3b, v63
	v_pk_mul_f32 v[112:113], v[24:25], v[232:233] op_sel_hi:[1,0]
	v_mul_f32_e32 v24, 0xbfb8aa3b, v2
	v_mul_f32_e32 v25, 0xbfb8aa3b, v3
	v_exp_f32_e32 v26, v26
	v_exp_f32_e32 v27, v27
	v_exp_f32_e32 v109, v107
	v_exp_f32_e32 v24, v24
	v_exp_f32_e32 v25, v25
	v_rcp_f32_e32 v107, v67
	v_add_f32_e32 v67, 1.0, v108
	v_add_f32_e32 v26, 1.0, v26
	v_add_f32_e32 v27, 1.0, v27
	v_rcp_f32_e32 v108, v67
	v_add_f32_e32 v67, 1.0, v109
	v_add_f32_e32 v24, 1.0, v24
	v_add_f32_e32 v25, 1.0, v25
	v_rcp_f32_e32 v26, v26
	v_rcp_f32_e32 v27, v27
	v_rcp_f32_e32 v109, v67
	v_pk_mul_f32 v[118:119], v[4:5], v[68:69] op_sel_hi:[1,0]
	v_pk_mul_f32 v[4:5], v[170:171], v[92:93]
	v_rcp_f32_e32 v24, v24
	v_rcp_f32_e32 v25, v25
	v_pk_mul_f32 v[116:117], v[6:7], v[68:69] op_sel_hi:[1,0]
	v_pk_mul_f32 v[6:7], v[168:169], v[90:91]
	v_pk_fma_f32 v[4:5], v[124:125], v[88:89], v[4:5]
	v_pk_fma_f32 v[6:7], v[126:127], v[86:87], v[6:7]
	v_pk_fma_f32 v[4:5], v[176:177], v[100:101], v[4:5]
	v_pk_mul_f32 v[106:107], v[60:61], v[106:107]
	v_pk_fma_f32 v[6:7], v[178:179], v[98:99], v[6:7]
	v_pk_add_f32 v[4:5], v[4:5], v[96:97]
	v_pk_mul_f32 v[0:1], v[0:1], v[26:27]
	v_pk_mul_f32 v[60:61], v[62:63], v[108:109]
	v_pk_mul_f32 v[62:63], v[104:105], v[106:107]
	v_pk_mul_f32 v[104:105], v[20:21], v[68:69] op_sel_hi:[1,0]
	v_pk_add_f32 v[6:7], v[6:7], v[94:95]
	v_pk_mul_f32 v[2:3], v[2:3], v[24:25]
	v_pk_mul_f32 v[0:1], v[0:1], v[4:5]
	v_pk_mul_f32 v[4:5], v[122:123], v[74:75]
	v_pk_mul_f32 v[114:115], v[22:23], v[68:69] op_sel_hi:[1,0]
	v_pk_mul_f32 v[2:3], v[2:3], v[6:7]
	v_pk_mul_f32 v[6:7], v[120:121], v[76:77]
	v_pk_fma_f32 v[4:5], v[104:105], v[70:71], v[4:5]
	v_pk_fma_f32 v[102:103], v[188:189], v[132:133], v[102:103]
	v_pk_fma_f32 v[6:7], v[114:115], v[72:73], v[6:7]
	v_pk_fma_f32 v[4:5], v[174:175], v[82:83], v[4:5]
	v_pk_add_f32 v[102:103], v[128:129], v[102:103]
	v_pk_fma_f32 v[6:7], v[172:173], v[84:85], v[6:7]
	v_pk_add_f32 v[4:5], v[4:5], v[78:79]
	v_pk_mul_f32 v[60:61], v[102:103], v[60:61]
	v_pk_mul_f32 v[68:69], v[30:31], v[66:67] op_sel_hi:[1,0]
	v_pk_mul_f32 v[102:103], v[28:29], v[66:67] op_sel_hi:[1,0]
	v_pk_mul_f32 v[28:29], v[18:19], v[66:67] op_sel_hi:[1,0]
	v_pk_mul_f32 v[30:31], v[16:17], v[66:67] op_sel_hi:[1,0]
	v_pk_add_f32 v[6:7], v[6:7], v[80:81]
	v_mul_f32_e32 v66, 0xbfb8aa3b, v4
	v_mul_f32_e32 v67, 0xbfb8aa3b, v5
	v_exp_f32_e32 v66, v66
	v_exp_f32_e32 v67, v67
	v_mul_f32_e32 v128, 0xbfb8aa3b, v6
	v_mul_f32_e32 v129, 0xbfb8aa3b, v7
	v_exp_f32_e32 v128, v128
	v_exp_f32_e32 v129, v129
	v_add_f32_e32 v66, 1.0, v66
	v_add_f32_e32 v67, 1.0, v67
	v_rcp_f32_e32 v66, v66
	v_rcp_f32_e32 v67, v67
	v_add_f32_e32 v128, 1.0, v128
	v_add_f32_e32 v129, 1.0, v129
	v_pk_mul_f32 v[26:27], v[126:127], v[90:91]
	v_rcp_f32_e32 v128, v128
	v_rcp_f32_e32 v129, v129
	v_pk_mul_f32 v[24:25], v[124:125], v[92:93]
	v_pk_fma_f32 v[26:27], v[118:119], v[86:87], v[26:27]
	v_pk_fma_f32 v[24:25], v[116:117], v[88:89], v[24:25]
	v_pk_fma_f32 v[26:27], v[168:169], v[98:99], v[26:27]
	v_pk_fma_f32 v[24:25], v[170:171], v[100:101], v[24:25]
	v_pk_add_f32 v[26:27], v[26:27], v[94:95]
	v_pk_mul_f32 v[66:67], v[4:5], v[66:67]
	v_pk_add_f32 v[24:25], v[24:25], v[96:97]
	v_pk_mul_f32 v[4:5], v[6:7], v[128:129]
	v_pk_mul_f32 v[6:7], v[66:67], v[26:27]
	v_pk_mul_f32 v[26:27], v[114:115], v[76:77]
	v_pk_mul_f32 v[4:5], v[4:5], v[24:25]
	v_pk_mul_f32 v[24:25], v[104:105], v[74:75]
	v_pk_fma_f32 v[26:27], v[110:111], v[72:73], v[26:27]
	v_pk_mul_f32 v[106:107], v[10:11], v[232:233] op_sel_hi:[1,0]
	v_pk_fma_f32 v[24:25], v[112:113], v[70:71], v[24:25]
	v_pk_fma_f32 v[26:27], v[120:121], v[84:85], v[26:27]
	v_pk_mul_f32 v[120:121], v[116:117], v[92:93]
	v_pk_fma_f32 v[24:25], v[122:123], v[82:83], v[24:25]
	v_pk_add_f32 v[26:27], v[26:27], v[80:81]
	v_pk_fma_f32 v[120:121], v[106:107], v[88:89], v[120:121]
	v_pk_add_f32 v[24:25], v[24:25], v[78:79]
	v_pk_fma_f32 v[120:121], v[124:125], v[100:101], v[120:121]
	v_mul_f32_e32 v124, 0xbfb8aa3b, v26
	v_mul_f32_e32 v125, 0xbfb8aa3b, v27
	v_mul_f32_e32 v122, 0xbfb8aa3b, v24
	v_mul_f32_e32 v123, 0xbfb8aa3b, v25
	v_exp_f32_e32 v124, v124
	v_exp_f32_e32 v125, v125
	v_exp_f32_e32 v122, v122
	v_exp_f32_e32 v123, v123
	v_add_f32_e32 v124, 1.0, v124
	v_add_f32_e32 v125, 1.0, v125
	v_add_f32_e32 v122, 1.0, v122
	v_add_f32_e32 v123, 1.0, v123
	v_rcp_f32_e32 v124, v124
	v_rcp_f32_e32 v125, v125
	v_rcp_f32_e32 v122, v122
	v_rcp_f32_e32 v123, v123
	v_pk_mul_f32 v[108:109], v[8:9], v[232:233] op_sel_hi:[1,0]
	v_pk_mul_f32 v[66:67], v[118:119], v[90:91]
	v_pk_add_f32 v[120:121], v[120:121], v[96:97]
	v_pk_fma_f32 v[66:67], v[108:109], v[86:87], v[66:67]
	v_pk_mul_f32 v[26:27], v[26:27], v[124:125]
	v_pk_fma_f32 v[66:67], v[126:127], v[98:99], v[66:67]
	v_pk_mul_f32 v[122:123], v[24:25], v[122:123]
	v_pk_add_f32 v[66:67], v[66:67], v[94:95]
	v_pk_mul_f32 v[24:25], v[26:27], v[120:121]
	v_pk_mul_f32 v[120:121], v[110:111], v[76:77]
	v_pk_mul_f32 v[26:27], v[122:123], v[66:67]
	v_pk_mul_f32 v[66:67], v[112:113], v[74:75]
	v_pk_fma_f32 v[120:121], v[68:69], v[72:73], v[120:121]
	v_pk_fma_f32 v[66:67], v[102:103], v[70:71], v[66:67]
	v_pk_fma_f32 v[114:115], v[114:115], v[84:85], v[120:121]
	v_pk_fma_f32 v[66:67], v[104:105], v[82:83], v[66:67]
	v_pk_add_f32 v[104:105], v[114:115], v[80:81]
	v_pk_mul_f32 v[114:115], v[108:109], v[90:91]
	v_pk_mul_f32 v[120:121], v[106:107], v[92:93]
	v_pk_add_f32 v[66:67], v[66:67], v[78:79]
	v_pk_fma_f32 v[120:121], v[28:29], v[88:89], v[120:121]
	v_pk_fma_f32 v[114:115], v[30:31], v[86:87], v[114:115]
	v_mul_f32_e32 v122, 0xbfb8aa3b, v66
	v_pk_fma_f32 v[116:117], v[116:117], v[100:101], v[120:121]
	v_pk_fma_f32 v[114:115], v[118:119], v[98:99], v[114:115]
	v_mul_f32_e32 v119, 0xbfb8aa3b, v67
	v_mul_f32_e32 v120, 0xbfb8aa3b, v104
	v_mul_f32_e32 v121, 0xbfb8aa3b, v105
	v_exp_f32_e32 v122, v122
	v_exp_f32_e32 v119, v119
	v_exp_f32_e32 v120, v120
	v_exp_f32_e32 v121, v121
	v_add_f32_e32 v118, 1.0, v122
	v_add_f32_e32 v119, 1.0, v119
	v_add_f32_e32 v120, 1.0, v120
	v_add_f32_e32 v121, 1.0, v121
	v_rcp_f32_e32 v118, v118
	v_rcp_f32_e32 v120, v120
	v_rcp_f32_e32 v121, v121
	v_rcp_f32_e32 v119, v119
	v_pk_add_f32 v[116:117], v[116:117], v[96:97]
	v_pk_add_f32 v[114:115], v[114:115], v[94:95]
	v_pk_mul_f32 v[104:105], v[104:105], v[120:121]
	v_pk_mul_f32 v[118:119], v[66:67], v[118:119]
	v_pk_mul_f32 v[66:67], v[104:105], v[116:117]
	v_pk_mul_f32 v[104:105], v[118:119], v[114:115]
	v_pk_mul_f32 v[114:115], v[68:69], v[76:77]
	v_pk_mul_f32 v[116:117], v[102:103], v[74:75]
	v_pk_fma_f32 v[114:115], v[162:163], v[72:73], v[114:115]
	v_pk_fma_f32 v[116:117], v[166:167], v[70:71], v[116:117]
	v_pk_fma_f32 v[110:111], v[110:111], v[84:85], v[114:115]
	v_pk_fma_f32 v[112:113], v[112:113], v[82:83], v[116:117]
	v_pk_mul_f32 v[114:115], v[28:29], v[92:93]
	v_pk_mul_f32 v[116:117], v[30:31], v[90:91]
	v_pk_add_f32 v[110:111], v[110:111], v[80:81]
	v_pk_add_f32 v[112:113], v[112:113], v[78:79]
	v_pk_fma_f32 v[116:117], v[64:65], v[86:87], v[116:117]
	v_pk_fma_f32 v[114:115], v[164:165], v[88:89], v[114:115]
	v_mul_f32_e32 v118, 0xbfb8aa3b, v112
	v_pk_fma_f32 v[106:107], v[106:107], v[100:101], v[114:115]
	v_pk_fma_f32 v[108:109], v[108:109], v[98:99], v[116:117]
	v_mul_f32_e32 v115, 0xbfb8aa3b, v113
	v_mul_f32_e32 v116, 0xbfb8aa3b, v110
	v_mul_f32_e32 v117, 0xbfb8aa3b, v111
	v_exp_f32_e32 v118, v118
	v_exp_f32_e32 v115, v115
	v_exp_f32_e32 v116, v116
	v_exp_f32_e32 v117, v117
	v_add_f32_e32 v114, 1.0, v118
	v_add_f32_e32 v115, 1.0, v115
	v_add_f32_e32 v116, 1.0, v116
	v_add_f32_e32 v117, 1.0, v117
	v_rcp_f32_e32 v114, v114
	v_rcp_f32_e32 v116, v116
	v_rcp_f32_e32 v117, v117
	v_rcp_f32_e32 v115, v115
	v_pk_add_f32 v[106:107], v[106:107], v[96:97]
	v_pk_add_f32 v[108:109], v[108:109], v[94:95]
	v_pk_mul_f32 v[110:111], v[110:111], v[116:117]
	v_pk_mul_f32 v[112:113], v[112:113], v[114:115]
	v_pk_mul_f32 v[106:107], v[110:111], v[106:107]
	v_pk_mul_f32 v[108:109], v[112:113], v[108:109]
	v_pk_mul_f32 v[110:111], v[162:163], v[76:77]
	v_pk_mul_f32 v[112:113], v[166:167], v[74:75]
	v_pk_fma_f32 v[110:111], v[156:157], v[72:73], v[110:111]
	v_pk_fma_f32 v[112:113], v[160:161], v[70:71], v[112:113]
	v_pk_fma_f32 v[68:69], v[68:69], v[84:85], v[110:111]
	v_pk_fma_f32 v[102:103], v[102:103], v[82:83], v[112:113]
	v_pk_mul_f32 v[110:111], v[164:165], v[92:93]
	v_pk_mul_f32 v[112:113], v[64:65], v[90:91]
	v_pk_add_f32 v[68:69], v[68:69], v[80:81]
	v_pk_add_f32 v[102:103], v[102:103], v[78:79]
	v_pk_fma_f32 v[112:113], v[134:135], v[86:87], v[112:113]
	v_pk_fma_f32 v[110:111], v[158:159], v[88:89], v[110:111]
	v_mul_f32_e32 v114, 0xbfb8aa3b, v102
	v_pk_fma_f32 v[28:29], v[28:29], v[100:101], v[110:111]
	v_pk_fma_f32 v[30:31], v[30:31], v[98:99], v[112:113]
	v_mul_f32_e32 v111, 0xbfb8aa3b, v103
	v_mul_f32_e32 v112, 0xbfb8aa3b, v68
	v_mul_f32_e32 v113, 0xbfb8aa3b, v69
	v_exp_f32_e32 v114, v114
	v_exp_f32_e32 v111, v111
	v_exp_f32_e32 v112, v112
	v_exp_f32_e32 v113, v113
	v_add_f32_e32 v110, 1.0, v114
	v_add_f32_e32 v111, 1.0, v111
	v_add_f32_e32 v112, 1.0, v112
	v_add_f32_e32 v113, 1.0, v113
	v_rcp_f32_e32 v110, v110
	v_rcp_f32_e32 v112, v112
	v_rcp_f32_e32 v113, v113
	v_rcp_f32_e32 v111, v111
	v_mov_b32_dpp v18, v182 row_shr:1 row_mask:0xf bank_mask:0xf bound_ctrl:1
	v_mov_b32_dpp v19, v183 row_shr:1 row_mask:0xf bank_mask:0xf bound_ctrl:1
	v_mov_b32_dpp v22, v180 row_shr:1 row_mask:0xf bank_mask:0xf bound_ctrl:1
	v_mov_b32_dpp v23, v181 row_shr:1 row_mask:0xf bank_mask:0xf bound_ctrl:1
	v_pk_add_f32 v[28:29], v[28:29], v[96:97]
	v_pk_add_f32 v[30:31], v[30:31], v[94:95]
	v_pk_mul_f32 v[68:69], v[68:69], v[112:113]
	v_pk_mul_f32 v[102:103], v[102:103], v[110:111]
	v_mov_b32_dpp v14, v174 row_shr:1 row_mask:0xf bank_mask:0xf bound_ctrl:1
	v_mov_b32_dpp v15, v175 row_shr:1 row_mask:0xf bank_mask:0xf bound_ctrl:1
	v_mov_b32_dpp v20, v172 row_shr:1 row_mask:0xf bank_mask:0xf bound_ctrl:1
	v_mov_b32_dpp v21, v173 row_shr:1 row_mask:0xf bank_mask:0xf bound_ctrl:1
	v_pk_mul_f32 v[28:29], v[68:69], v[28:29]
	v_pk_mul_f32 v[30:31], v[102:103], v[30:31]
	v_pk_mul_f32 v[68:69], v[70:71], v[18:19]
	v_pk_mul_f32 v[102:103], v[72:73], v[22:23]
	v_pk_mul_f32 v[18:19], v[74:75], v[18:19]
	v_pk_mul_f32 v[22:23], v[76:77], v[22:23]
	v_pk_fma_f32 v[14:15], v[70:71], v[14:15], v[18:19]
	v_pk_fma_f32 v[20:21], v[72:73], v[20:21], v[22:23]
	v_mov_b32_dpp v10, v178 row_shr:1 row_mask:0xf bank_mask:0xf bound_ctrl:1
	v_mov_b32_dpp v11, v179 row_shr:1 row_mask:0xf bank_mask:0xf bound_ctrl:1
	v_mov_b32_dpp v16, v176 row_shr:1 row_mask:0xf bank_mask:0xf bound_ctrl:1
	v_mov_b32_dpp v17, v177 row_shr:1 row_mask:0xf bank_mask:0xf bound_ctrl:1
	v_pk_fma_f32 v[68:69], v[160:161], v[74:75], v[68:69]
	v_pk_fma_f32 v[14:15], v[160:161], v[82:83], v[14:15]
	v_pk_fma_f32 v[18:19], v[156:157], v[84:85], v[20:21]
	v_mov_b32_dpp v8, v168 row_shr:1 row_mask:0xf bank_mask:0xf bound_ctrl:1
	v_mov_b32_dpp v9, v169 row_shr:1 row_mask:0xf bank_mask:0xf bound_ctrl:1
	v_mov_b32_dpp v12, v170 row_shr:1 row_mask:0xf bank_mask:0xf bound_ctrl:1
	v_mov_b32_dpp v13, v171 row_shr:1 row_mask:0xf bank_mask:0xf bound_ctrl:1
	v_pk_fma_f32 v[68:69], v[166:167], v[82:83], v[68:69]
	v_pk_mul_f32 v[110:111], v[88:89], v[16:17]
	v_pk_mul_f32 v[112:113], v[86:87], v[10:11]
	v_pk_add_f32 v[18:19], v[80:81], v[18:19]
	v_pk_add_f32 v[14:15], v[78:79], v[14:15]
	v_pk_mul_f32 v[16:17], v[92:93], v[16:17]
	v_pk_mul_f32 v[10:11], v[90:91], v[10:11]
	v_pk_add_f32 v[68:69], v[78:79], v[68:69]
	v_pk_fma_f32 v[8:9], v[86:87], v[8:9], v[10:11]
	v_pk_fma_f32 v[10:11], v[88:89], v[12:13], v[16:17]
	v_mul_f32_e32 v12, 0xbfb8aa3b, v14
	v_mul_f32_e32 v13, 0xbfb8aa3b, v15
	v_mul_f32_e32 v16, 0xbfb8aa3b, v18
	v_mul_f32_e32 v17, 0xbfb8aa3b, v19
	v_mul_f32_e32 v114, 0xbfb8aa3b, v68
	v_mul_f32_e32 v115, 0xbfb8aa3b, v69
	v_exp_f32_e32 v12, v12
	v_exp_f32_e32 v13, v13
	v_exp_f32_e32 v16, v16
	v_exp_f32_e32 v17, v17
	v_exp_f32_e32 v114, v114
	v_exp_f32_e32 v115, v115
	v_pk_fma_f32 v[102:103], v[156:157], v[76:77], v[102:103]
	v_pk_fma_f32 v[112:113], v[134:135], v[90:91], v[112:113]
	v_pk_fma_f32 v[102:103], v[162:163], v[84:85], v[102:103]
	v_add_f32_e32 v12, 1.0, v12
	v_pk_add_f32 v[102:103], v[80:81], v[102:103]
	v_add_f32_e32 v13, 1.0, v13
	v_add_f32_e32 v16, 1.0, v16
	v_add_f32_e32 v17, 1.0, v17
	v_pk_fma_f32 v[64:65], v[64:65], v[98:99], v[112:113]
	v_add_f32_e32 v112, 1.0, v114
	v_add_f32_e32 v113, 1.0, v115
	v_mul_f32_e32 v114, 0xbfb8aa3b, v102
	v_mul_f32_e32 v115, 0xbfb8aa3b, v103
	v_rcp_f32_e32 v12, v12
	v_rcp_f32_e32 v13, v13
	v_rcp_f32_e32 v16, v16
	v_rcp_f32_e32 v17, v17
	v_exp_f32_e32 v114, v114
	v_exp_f32_e32 v115, v115
	v_pk_fma_f32 v[10:11], v[158:159], v[100:101], v[10:11]
	v_pk_fma_f32 v[8:9], v[134:135], v[98:99], v[8:9]
	v_pk_add_f32 v[10:11], v[96:97], v[10:11]
	v_pk_add_f32 v[8:9], v[94:95], v[8:9]
	v_pk_mul_f32 v[12:13], v[14:15], v[12:13]
	v_pk_mul_f32 v[14:15], v[18:19], v[16:17]
	v_add_f32_e32 v114, 1.0, v114
	v_add_f32_e32 v115, 1.0, v115
	v_pk_mul_f32 v[14:15], v[10:11], v[14:15]
	v_pk_mul_f32 v[10:11], v[8:9], v[12:13]
	v_mov_b64_e32 v[12:13], s[16:17]
	v_readfirstlane_b32 s62, v152
	v_readfirstlane_b32 s63, v154
	v_mbcnt_lo_u32_b32 v176, -1, 0
	v_mbcnt_hi_u32_b32 v176, -1, v176
	v_lshrrev_b32_e32 v177, 2, v176
	v_and_b32_e32 v178, 3, v176
	s_mul_i32 s62, s62, 0x1600
	s_lshl_b32 s63, s63, 1
	s_add_i32 s62, s62, s63
	v_mul_u32_u24_e32 v179, 0xb000, v177
	v_lshl_add_u32 v179, v178, 4, v179
	v_add_u32_e32 v179, s62, v179
	s_lshr_b32 s63, s33, 6
	s_mulk_i32 s63, 0x500
	s_add_i32 s63, s63, 0x20400
	v_mul_u32_u24_e32 v188, 0x50, v177
	v_lshl_add_u32 v188, v178, 4, v188
	v_add_u32_e32 v188, s63, v188
	v_and_b32_e32 v177, 15, v176
	v_lshrrev_b32_e32 v178, 4, v176
	v_mul_u32_u24_e32 v189, 0x50, v177
	v_lshl_add_u32 v189, v178, 4, v189
	v_add_u32_e32 v189, s63, v189
	v_rcp_f32_e32 v112, v112
	v_rcp_f32_e32 v113, v113
	v_rcp_f32_e32 v114, v114
	v_rcp_f32_e32 v115, v115
	v_cvt_pk_bf16_f32 v8, v62, v63
	v_cvt_pk_bf16_f32 v9, v60, v61
	v_cvt_pk_bf16_f32 v10, v10, v11
	v_cvt_pk_bf16_f32 v11, v14, v15
	v_mad_i64_i32 v[14:15], s[26:27], v152, s93, v[12:13]
	v_lshlrev_b64 v[16:17], 1, v[154:155]
	v_lshl_add_u64 v[14:15], v[14:15], 0, v[16:17]
	v_pk_fma_f32 v[110:111], v[158:159], v[92:93], v[110:111]
	ds_write_b128 v189, v[8:11]
	ds_read_b128 v[180:183], v188
	s_waitcnt lgkmcnt(0)
	global_store_dwordx4 v179, v[180:183], s[16:17]
	v_or_b32_e32 v14, 1, v152
	v_pk_fma_f32 v[110:111], v[164:165], v[100:101], v[110:111]
	v_mad_i64_i32 v[14:15], s[26:27], v14, s93, v[12:13]
	v_pk_add_f32 v[64:65], v[94:95], v[64:65]
	v_pk_add_f32 v[110:111], v[96:97], v[110:111]
	v_pk_mul_f32 v[68:69], v[68:69], v[112:113]
	v_pk_mul_f32 v[102:103], v[102:103], v[114:115]
	v_lshl_add_u64 v[14:15], v[14:15], 0, v[16:17]
	v_pk_mul_f32 v[102:103], v[110:111], v[102:103]
	v_pk_mul_f32 v[64:65], v[64:65], v[68:69]
	v_cvt_pk_bf16_f32 v8, v58, v59
	v_cvt_pk_bf16_f32 v9, v56, v57
	s_mov_b64 s[6:7], -1
	v_cvt_pk_bf16_f32 v10, v64, v65
	v_cvt_pk_bf16_f32 v11, v102, v103
	ds_write_b128 v189, v[8:11]
	ds_read_b128 v[184:187], v188
	v_add_u32_e32 v190, 0x1600, v179
	s_waitcnt lgkmcnt(0)
	global_store_dwordx4 v190, v[184:187], s[16:17]
	v_or_b32_e32 v14, 2, v152
	v_mad_i64_i32 v[14:15], s[26:27], v14, s93, v[12:13]
	v_lshl_add_u64 v[14:15], v[14:15], 0, v[16:17]
	v_cvt_pk_bf16_f32 v8, v54, v55
	v_cvt_pk_bf16_f32 v9, v52, v53
	v_cvt_pk_bf16_f32 v10, v30, v31
	v_cvt_pk_bf16_f32 v11, v28, v29
	ds_write_b128 v189, v[8:11]
	ds_read_b128 v[180:183], v188
	v_add_u32_e32 v190, 0x2c00, v179
	s_waitcnt lgkmcnt(0)
	global_store_dwordx4 v190, v[180:183], s[16:17]
	v_or_b32_e32 v14, 3, v152
	v_mad_i64_i32 v[14:15], s[26:27], v14, s93, v[12:13]
	v_lshl_add_u64 v[14:15], v[14:15], 0, v[16:17]
	v_cvt_pk_bf16_f32 v8, v50, v51
	v_cvt_pk_bf16_f32 v9, v48, v49
	v_cvt_pk_bf16_f32 v10, v108, v109
	v_cvt_pk_bf16_f32 v11, v106, v107
	ds_write_b128 v189, v[8:11]
	ds_read_b128 v[184:187], v188
	v_add_u32_e32 v190, 0x4200, v179
	s_waitcnt lgkmcnt(0)
	global_store_dwordx4 v190, v[184:187], s[16:17]
	v_or_b32_e32 v14, 4, v152
	v_mad_i64_i32 v[14:15], s[26:27], v14, s93, v[12:13]
	v_lshl_add_u64 v[14:15], v[14:15], 0, v[16:17]
	v_cvt_pk_bf16_f32 v8, v46, v47
	v_cvt_pk_bf16_f32 v9, v44, v45
	v_cvt_pk_bf16_f32 v10, v104, v105
	v_cvt_pk_bf16_f32 v11, v66, v67
	ds_write_b128 v189, v[8:11]
	ds_read_b128 v[180:183], v188
	v_add_u32_e32 v190, 0x5800, v179
	s_waitcnt lgkmcnt(0)
	global_store_dwordx4 v190, v[180:183], s[16:17]
	v_or_b32_e32 v14, 5, v152
	v_mad_i64_i32 v[14:15], s[26:27], v14, s93, v[12:13]
	v_cvt_pk_bf16_f32 v8, v42, v43
	v_cvt_pk_bf16_f32 v9, v40, v41
	v_cvt_pk_bf16_f32 v10, v26, v27
	v_cvt_pk_bf16_f32 v11, v24, v25
	v_lshl_add_u64 v[14:15], v[14:15], 0, v[16:17]
	ds_write_b128 v189, v[8:11]
	ds_read_b128 v[184:187], v188
	v_add_u32_e32 v190, 0x6e00, v179
	s_waitcnt lgkmcnt(0)
	global_store_dwordx4 v190, v[184:187], s[16:17]
	s_nop 1
	v_cvt_pk_bf16_f32 v8, v38, v39
	v_cvt_pk_bf16_f32 v9, v36, v37
	v_cvt_pk_bf16_f32 v10, v6, v7
	v_cvt_pk_bf16_f32 v11, v4, v5
	v_or_b32_e32 v4, 6, v152
	v_mad_i64_i32 v[4:5], s[26:27], v4, s93, v[12:13]
	v_lshl_add_u64 v[4:5], v[4:5], 0, v[16:17]
	ds_write_b128 v189, v[8:11]
	ds_read_b128 v[180:183], v188
	v_add_u32_e32 v190, 0x8400, v179
	s_waitcnt lgkmcnt(0)
	global_store_dwordx4 v190, v[180:183], s[16:17]
	v_cvt_pk_bf16_f32 v4, v34, v35
	v_cvt_pk_bf16_f32 v5, v32, v33
	v_cvt_pk_bf16_f32 v6, v2, v3
	v_cvt_pk_bf16_f32 v7, v0, v1
	v_or_b32_e32 v0, 7, v152
	v_mad_i64_i32 v[0:1], s[26:27], v0, s93, v[12:13]
	v_lshl_add_u64 v[0:1], v[0:1], 0, v[16:17]
	ds_write_b128 v189, v[4:7]
	ds_read_b128 v[184:187], v188
	v_add_u32_e32 v190, 0x9a00, v179
	s_waitcnt lgkmcnt(0)
	global_store_dwordx4 v190, v[184:187], s[16:17]
	s_cbranch_vccnz .LBB0_878
	s_andn2_b64 vcc, exec, s[0:1]
	s_cbranch_vccnz .LBB0_877
	s_barrier
	s_branch .LBB0_877

	.amdhsa_kernel _Z9hymba_fwd4Args
		.amdhsa_group_segment_fixed_size 0
		.amdhsa_private_segment_fixed_size 0
		.amdhsa_kernarg_size 464
		.amdhsa_user_sgpr_count 2
		.amdhsa_user_sgpr_dispatch_ptr 0
		.amdhsa_user_sgpr_queue_ptr 0
		.amdhsa_user_sgpr_kernarg_segment_ptr 1
		.amdhsa_user_sgpr_dispatch_id 0
		.amdhsa_user_sgpr_kernarg_preload_length 0
		.amdhsa_user_sgpr_kernarg_preload_offset 0
		.amdhsa_user_sgpr_private_segment_size 0
		.amdhsa_uses_dynamic_stack 0
		.amdhsa_enable_private_segment 0
		.amdhsa_system_sgpr_workgroup_id_x 1
		.amdhsa_system_sgpr_workgroup_id_y 0
		.amdhsa_system_sgpr_workgroup_id_z 0
		.amdhsa_system_sgpr_workgroup_info 0
		.amdhsa_system_vgpr_workitem_id 2
		.amdhsa_next_free_vgpr 256
		.amdhsa_next_free_sgpr 102
		.amdhsa_accum_offset 256
		.amdhsa_reserve_vcc 1
		.amdhsa_float_round_mode_32 0
		.amdhsa_float_round_mode_16_64 0
		.amdhsa_float_denorm_mode_32 3
		.amdhsa_float_denorm_mode_16_64 3
		.amdhsa_dx10_clamp 1
		.amdhsa_ieee_mode 1
		.amdhsa_fp16_overflow 0
		.amdhsa_tg_split 0
		.amdhsa_exception_fp_ieee_invalid_op 0
		.amdhsa_exception_fp_denorm_src 0
		.amdhsa_exception_fp_ieee_div_zero 0
		.amdhsa_exception_fp_ieee_overflow 0
		.amdhsa_exception_fp_ieee_underflow 0
		.amdhsa_exception_fp_ieee_inexact 0
		.amdhsa_exception_int_div_zero 0
	.end_amdhsa_kernel

amdhsa.kernels:
  - .agpr_count:     0
    .args:
      - .offset:         0
        .size:           208
        .value_kind:     by_value
      - .offset:         208
        .size:           4
        .value_kind:     hidden_block_count_x
      - .offset:         212
        .size:           4
        .value_kind:     hidden_block_count_y
      - .offset:         216
        .size:           4
        .value_kind:     hidden_block_count_z
      - .offset:         220
        .size:           2
        .value_kind:     hidden_group_size_x
      - .offset:         222
        .size:           2
        .value_kind:     hidden_group_size_y
      - .offset:         224
        .size:           2
        .value_kind:     hidden_group_size_z
      - .offset:         226
        .size:           2
        .value_kind:     hidden_remainder_x
      - .offset:         228
        .size:           2
        .value_kind:     hidden_remainder_y
      - .offset:         230
        .size:           2
        .value_kind:     hidden_remainder_z
      - .offset:         248
        .size:           8
        .value_kind:     hidden_global_offset_x
      - .offset:         256
        .size:           8
        .value_kind:     hidden_global_offset_y
      - .offset:         264
        .size:           8
        .value_kind:     hidden_global_offset_z
      - .offset:         272
        .size:           2
        .value_kind:     hidden_grid_dims
      - .offset:         296
        .size:           8
        .value_kind:     hidden_multigrid_sync_arg
      - .offset:         328
        .size:           4
        .value_kind:     hidden_dynamic_lds_size
    .group_segment_fixed_size: 0
    .kernarg_segment_align: 8
    .kernarg_segment_size: 464
    .language:       OpenCL C
    .language_version:
      - 2
      - 0
    .max_flat_workgroup_size: 512
    .name:           _Z9hymba_fwd4Args
    .private_segment_fixed_size: 0
    .sgpr_count:     108
    .sgpr_spill_count: 32
    .symbol:         _Z9hymba_fwd4Args.kd
    .uniform_work_group_size: 1
    .uses_dynamic_stack: false
    .vgpr_count:     256
    .vgpr_spill_count: 0
    .wavefront_size: 64
